# combine gate-load hoist; dn_chunk_pre rhs-init LDS batching; GLA gate-row prefetch one chunk ahead
# speedup vs baseline: 1.0272x; 1.0117x over previous
.LBB0_466:
	s_or_b64 exec, exec, s[4:5]
	v_add_u32_e32 v127, v56, v91
	s_and_b64 vcc, exec, s[44:45]
	s_cbranch_vccz .Lxi_vpath
	ds_read_b32 v218, v57 offset:51456
	ds_read_u16 v226, v62
	ds_read_b32 v234, v57 offset:51200
	ds_read_b32 v219, v57 offset:51460
	ds_read_u16 v227, v64
	ds_read_b32 v235, v57 offset:51204
	ds_read_b32 v220, v57 offset:51464
	ds_read_u16 v228, v66
	ds_read_b32 v236, v57 offset:51208
	ds_read_b32 v221, v57 offset:51468
	ds_read_u16 v229, v68
	ds_read_b32 v237, v57 offset:51212
	ds_read_b32 v222, v57 offset:51488
	ds_read_u16 v230, v70
	ds_read_b32 v238, v57 offset:51232
	ds_read_b32 v223, v57 offset:51492
	ds_read_u16 v231, v72
	ds_read_b32 v239, v57 offset:51236
	ds_read_b32 v224, v57 offset:51496
	ds_read_u16 v232, v74
	ds_read_b32 v240, v57 offset:51240
	ds_read_b32 v225, v57 offset:51500
	ds_read_u16 v233, v76
	ds_read_b32 v241, v57 offset:51244
	s_waitcnt lgkmcnt(0)
	v_lshlrev_b32_e32 v226, 16, v226
	v_mul_f32_e32 v218, v218, v226
	v_mul_f32_e32 v234, 0x3fb8aa3b, v234
	v_exp_f32_e32 v234, v234
	v_lshlrev_b32_e32 v227, 16, v227
	v_mul_f32_e32 v219, v219, v227
	v_mul_f32_e32 v235, 0x3fb8aa3b, v235
	v_exp_f32_e32 v235, v235
	v_lshlrev_b32_e32 v228, 16, v228
	v_mul_f32_e32 v220, v220, v228
	v_mul_f32_e32 v236, 0x3fb8aa3b, v236
	v_exp_f32_e32 v236, v236
	v_lshlrev_b32_e32 v229, 16, v229
	v_mul_f32_e32 v221, v221, v229
	v_mul_f32_e32 v237, 0x3fb8aa3b, v237
	v_exp_f32_e32 v237, v237
	v_lshlrev_b32_e32 v230, 16, v230
	v_mul_f32_e32 v222, v222, v230
	v_mul_f32_e32 v238, 0x3fb8aa3b, v238
	v_exp_f32_e32 v238, v238
	v_lshlrev_b32_e32 v231, 16, v231
	v_mul_f32_e32 v223, v223, v231
	v_mul_f32_e32 v239, 0x3fb8aa3b, v239
	v_exp_f32_e32 v239, v239
	v_lshlrev_b32_e32 v232, 16, v232
	v_mul_f32_e32 v224, v224, v232
	v_mul_f32_e32 v240, 0x3fb8aa3b, v240
	v_exp_f32_e32 v240, v240
	v_lshlrev_b32_e32 v233, 16, v233
	v_mul_f32_e32 v225, v225, v233
	v_mul_f32_e32 v241, 0x3fb8aa3b, v241
	v_exp_f32_e32 v241, v241
	s_nop 0
	v_mul_f32_e32 v4, v234, v218
	v_mul_f32_e32 v5, v235, v219
	v_mul_f32_e32 v6, v236, v220
	v_mul_f32_e32 v7, v237, v221
	v_mul_f32_e32 v8, v238, v222
	v_mul_f32_e32 v9, v239, v223
	v_mul_f32_e32 v10, v240, v224
	v_mul_f32_e32 v11, v241, v225
	ds_read_b32 v218, v57 offset:51520
	ds_read_u16 v226, v78
	ds_read_b32 v234, v57 offset:51264
	ds_read_b32 v219, v57 offset:51524
	ds_read_u16 v227, v80
	ds_read_b32 v235, v57 offset:51268
	ds_read_b32 v220, v57 offset:51528
	ds_read_u16 v228, v82
	ds_read_b32 v236, v57 offset:51272
	ds_read_b32 v221, v57 offset:51532
	ds_read_u16 v229, v84
	ds_read_b32 v237, v57 offset:51276
	ds_read_b32 v222, v57 offset:51552
	ds_read_u16 v230, v86
	ds_read_b32 v238, v57 offset:51296
	ds_read_b32 v223, v57 offset:51556
	ds_read_u16 v231, v88
	ds_read_b32 v239, v57 offset:51300
	ds_read_b32 v224, v57 offset:51560
	ds_read_u16 v232, v90
	ds_read_b32 v240, v57 offset:51304
	ds_read_b32 v225, v57 offset:51564
	ds_read_u16 v233, v92
	ds_read_b32 v241, v57 offset:51308
	s_waitcnt lgkmcnt(0)
	v_lshlrev_b32_e32 v226, 16, v226
	v_mul_f32_e32 v218, v218, v226
	v_mul_f32_e32 v234, 0x3fb8aa3b, v234
	v_exp_f32_e32 v234, v234
	v_lshlrev_b32_e32 v227, 16, v227
	v_mul_f32_e32 v219, v219, v227
	v_mul_f32_e32 v235, 0x3fb8aa3b, v235
	v_exp_f32_e32 v235, v235
	v_lshlrev_b32_e32 v228, 16, v228
	v_mul_f32_e32 v220, v220, v228
	v_mul_f32_e32 v236, 0x3fb8aa3b, v236
	v_exp_f32_e32 v236, v236
	v_lshlrev_b32_e32 v229, 16, v229
	v_mul_f32_e32 v221, v221, v229
	v_mul_f32_e32 v237, 0x3fb8aa3b, v237
	v_exp_f32_e32 v237, v237
	v_lshlrev_b32_e32 v230, 16, v230
	v_mul_f32_e32 v222, v222, v230
	v_mul_f32_e32 v238, 0x3fb8aa3b, v238
	v_exp_f32_e32 v238, v238
	v_lshlrev_b32_e32 v231, 16, v231
	v_mul_f32_e32 v223, v223, v231
	v_mul_f32_e32 v239, 0x3fb8aa3b, v239
	v_exp_f32_e32 v239, v239
	v_lshlrev_b32_e32 v232, 16, v232
	v_mul_f32_e32 v224, v224, v232
	v_mul_f32_e32 v240, 0x3fb8aa3b, v240
	v_exp_f32_e32 v240, v240
	v_lshlrev_b32_e32 v233, 16, v233
	v_mul_f32_e32 v225, v225, v233
	v_mul_f32_e32 v241, 0x3fb8aa3b, v241
	v_exp_f32_e32 v241, v241
	s_nop 0
	v_mul_f32_e32 v111, v234, v218
	v_mul_f32_e32 v112, v235, v219
	v_mul_f32_e32 v113, v236, v220
	v_mul_f32_e32 v114, v237, v221
	v_mul_f32_e32 v119, v238, v222
	v_mul_f32_e32 v120, v239, v223
	v_mul_f32_e32 v121, v240, v224
	v_mul_f32_e32 v122, v241, v225
	ds_read_b32 v218, v57 offset:51584
	ds_read_u16 v226, v127 offset:1104
	ds_read_b32 v234, v57 offset:51328
	ds_read_b32 v219, v57 offset:51588
	ds_read_u16 v227, v127 offset:1376
	ds_read_b32 v235, v57 offset:51332
	ds_read_b32 v220, v57 offset:51592
	ds_read_u16 v228, v127 offset:1648
	ds_read_b32 v236, v57 offset:51336
	ds_read_b32 v221, v57 offset:51596
	ds_read_u16 v229, v127 offset:1920
	ds_read_b32 v237, v57 offset:51340
	ds_read_b32 v222, v57 offset:51616
	ds_read_u16 v230, v127 offset:3280
	ds_read_b32 v238, v57 offset:51360
	ds_read_b32 v223, v57 offset:51620
	ds_read_u16 v231, v127 offset:3552
	ds_read_b32 v239, v57 offset:51364
	ds_read_b32 v224, v57 offset:51624
	ds_read_u16 v232, v127 offset:3824
	ds_read_b32 v240, v57 offset:51368
	ds_read_b32 v225, v57 offset:51628
	ds_read_u16 v233, v127 offset:4096
	ds_read_b32 v241, v57 offset:51372
	s_waitcnt lgkmcnt(0)
	v_lshlrev_b32_e32 v226, 16, v226
	v_mul_f32_e32 v218, v218, v226
	v_mul_f32_e32 v234, 0x3fb8aa3b, v234
	v_exp_f32_e32 v234, v234
	v_lshlrev_b32_e32 v227, 16, v227
	v_mul_f32_e32 v219, v219, v227
	v_mul_f32_e32 v235, 0x3fb8aa3b, v235
	v_exp_f32_e32 v235, v235
	v_lshlrev_b32_e32 v228, 16, v228
	v_mul_f32_e32 v220, v220, v228
	v_mul_f32_e32 v236, 0x3fb8aa3b, v236
	v_exp_f32_e32 v236, v236
	v_lshlrev_b32_e32 v229, 16, v229
	v_mul_f32_e32 v221, v221, v229
	v_mul_f32_e32 v237, 0x3fb8aa3b, v237
	v_exp_f32_e32 v237, v237
	v_lshlrev_b32_e32 v230, 16, v230
	v_mul_f32_e32 v222, v222, v230
	v_mul_f32_e32 v238, 0x3fb8aa3b, v238
	v_exp_f32_e32 v238, v238
	v_lshlrev_b32_e32 v231, 16, v231
	v_mul_f32_e32 v223, v223, v231
	v_mul_f32_e32 v239, 0x3fb8aa3b, v239
	v_exp_f32_e32 v239, v239
	v_lshlrev_b32_e32 v232, 16, v232
	v_mul_f32_e32 v224, v224, v232
	v_mul_f32_e32 v240, 0x3fb8aa3b, v240
	v_exp_f32_e32 v240, v240
	v_lshlrev_b32_e32 v233, 16, v233
	v_mul_f32_e32 v225, v225, v233
	v_mul_f32_e32 v241, 0x3fb8aa3b, v241
	v_exp_f32_e32 v241, v241
	s_nop 0
	v_mul_f32_e32 v123, v234, v218
	v_mul_f32_e32 v124, v235, v219
	v_mul_f32_e32 v125, v236, v220
	v_mul_f32_e32 v126, v237, v221
	v_mul_f32_e32 v115, v238, v222
	v_mul_f32_e32 v116, v239, v223
	v_mul_f32_e32 v117, v240, v224
	v_mul_f32_e32 v118, v241, v225
	ds_read_b32 v218, v57 offset:51648
	ds_read_u16 v226, v127 offset:5456
	ds_read_b32 v234, v57 offset:51392
	ds_read_b32 v219, v57 offset:51652
	ds_read_u16 v227, v127 offset:5728
	ds_read_b32 v235, v57 offset:51396
	ds_read_b32 v220, v57 offset:51656
	ds_read_u16 v228, v127 offset:6000
	ds_read_b32 v236, v57 offset:51400
	ds_read_b32 v221, v57 offset:51660
	ds_read_u16 v229, v127 offset:6272
	ds_read_b32 v237, v57 offset:51404
	ds_read_b32 v222, v57 offset:51680
	ds_read_u16 v230, v127 offset:7632
	ds_read_b32 v238, v57 offset:51424
	ds_read_b32 v223, v57 offset:51684
	ds_read_u16 v231, v127 offset:7904
	ds_read_b32 v239, v57 offset:51428
	ds_read_b32 v224, v57 offset:51688
	ds_read_u16 v232, v127 offset:8176
	ds_read_b32 v240, v57 offset:51432
	s_waitcnt lgkmcnt(0)
	v_lshlrev_b32_e32 v226, 16, v226
	v_mul_f32_e32 v218, v218, v226
	v_mul_f32_e32 v234, 0x3fb8aa3b, v234
	v_exp_f32_e32 v234, v234
	v_lshlrev_b32_e32 v227, 16, v227
	v_mul_f32_e32 v219, v219, v227
	v_mul_f32_e32 v235, 0x3fb8aa3b, v235
	v_exp_f32_e32 v235, v235
	v_lshlrev_b32_e32 v228, 16, v228
	v_mul_f32_e32 v220, v220, v228
	v_mul_f32_e32 v236, 0x3fb8aa3b, v236
	v_exp_f32_e32 v236, v236
	v_lshlrev_b32_e32 v229, 16, v229
	v_mul_f32_e32 v221, v221, v229
	v_mul_f32_e32 v237, 0x3fb8aa3b, v237
	v_exp_f32_e32 v237, v237
	v_lshlrev_b32_e32 v230, 16, v230
	v_mul_f32_e32 v222, v222, v230
	v_mul_f32_e32 v238, 0x3fb8aa3b, v238
	v_exp_f32_e32 v238, v238
	v_lshlrev_b32_e32 v231, 16, v231
	v_mul_f32_e32 v223, v223, v231
	v_mul_f32_e32 v239, 0x3fb8aa3b, v239
	v_exp_f32_e32 v239, v239
	v_lshlrev_b32_e32 v232, 16, v232
	v_mul_f32_e32 v224, v224, v232
	v_mul_f32_e32 v240, 0x3fb8aa3b, v240
	v_exp_f32_e32 v240, v240
	s_nop 0
	v_mul_f32_e32 v15, v234, v218
	v_mul_f32_e32 v14, v235, v219
	v_mul_f32_e32 v13, v236, v220
	v_mul_f32_e32 v12, v237, v221
	v_mul_f32_e32 v3, v238, v222
	v_mul_f32_e32 v2, v239, v223
	v_mul_f32_e32 v1, v240, v224
	s_branch .Lxi_done
.Lxi_vpath:
	ds_read_b32 v218, v57 offset:51456
	ds_read_u16 v226, v61 offset:17408
	ds_read_b32 v219, v57 offset:51460
	ds_read_u16 v227, v63 offset:17408
	ds_read_b32 v220, v57 offset:51464
	v_add_u32_e32 v228, v56, v65
	ds_read_u16 v228, v228 offset:17408
	ds_read_b32 v221, v57 offset:51468
	v_add_u32_e32 v229, v56, v67
	ds_read_u16 v229, v229 offset:17408
	ds_read_b32 v222, v57 offset:51488
	v_add_u32_e32 v230, v56, v69
	ds_read_u16 v230, v230 offset:17408
	ds_read_b32 v223, v57 offset:51492
	v_add_u32_e32 v231, v56, v71
	ds_read_u16 v231, v231 offset:17408
	ds_read_b32 v224, v57 offset:51496
	v_add_u32_e32 v232, v56, v73
	ds_read_u16 v232, v232 offset:17408
	ds_read_b32 v225, v57 offset:51500
	v_add_u32_e32 v233, v56, v75
	ds_read_u16 v233, v233 offset:17408
	s_waitcnt lgkmcnt(0)
	v_lshlrev_b32_e32 v226, 16, v226
	v_lshlrev_b32_e32 v227, 16, v227
	v_lshlrev_b32_e32 v228, 16, v228
	v_lshlrev_b32_e32 v229, 16, v229
	v_lshlrev_b32_e32 v230, 16, v230
	v_lshlrev_b32_e32 v231, 16, v231
	v_lshlrev_b32_e32 v232, 16, v232
	v_lshlrev_b32_e32 v233, 16, v233
	v_mul_f32_e32 v4, v218, v226
	v_mul_f32_e32 v5, v219, v227
	v_mul_f32_e32 v6, v220, v228
	v_mul_f32_e32 v7, v221, v229
	v_mul_f32_e32 v8, v222, v230
	v_mul_f32_e32 v9, v223, v231
	v_mul_f32_e32 v10, v224, v232
	v_mul_f32_e32 v11, v225, v233
	ds_read_b32 v218, v57 offset:51520
	v_add_u32_e32 v226, v56, v77
	ds_read_u16 v226, v226 offset:17408
	ds_read_b32 v219, v57 offset:51524
	v_add_u32_e32 v227, v56, v79
	ds_read_u16 v227, v227 offset:17408
	ds_read_b32 v220, v57 offset:51528
	v_add_u32_e32 v228, v56, v81
	ds_read_u16 v228, v228 offset:17408
	ds_read_b32 v221, v57 offset:51532
	v_add_u32_e32 v229, v56, v83
	ds_read_u16 v229, v229 offset:17408
	ds_read_b32 v222, v57 offset:51552
	v_add_u32_e32 v230, v56, v85
	ds_read_u16 v230, v230 offset:17408
	ds_read_b32 v223, v57 offset:51556
	v_add_u32_e32 v231, v56, v87
	ds_read_u16 v231, v231 offset:17408
	ds_read_b32 v224, v57 offset:51560
	v_add_u32_e32 v232, v56, v89
	ds_read_u16 v232, v232 offset:17408
	ds_read_b32 v225, v57 offset:51564
	ds_read_u16 v233, v127 offset:17408
	s_waitcnt lgkmcnt(0)
	v_lshlrev_b32_e32 v226, 16, v226
	v_lshlrev_b32_e32 v227, 16, v227
	v_lshlrev_b32_e32 v228, 16, v228
	v_lshlrev_b32_e32 v229, 16, v229
	v_lshlrev_b32_e32 v230, 16, v230
	v_lshlrev_b32_e32 v231, 16, v231
	v_lshlrev_b32_e32 v232, 16, v232
	v_lshlrev_b32_e32 v233, 16, v233
	v_mul_f32_e32 v111, v218, v226
	v_mul_f32_e32 v112, v219, v227
	v_mul_f32_e32 v113, v220, v228
	v_mul_f32_e32 v114, v221, v229
	v_mul_f32_e32 v119, v222, v230
	v_mul_f32_e32 v120, v223, v231
	v_mul_f32_e32 v121, v224, v232
	v_mul_f32_e32 v122, v225, v233
	ds_read_b32 v218, v57 offset:51584
	ds_read_u16 v226, v127 offset:18768
	ds_read_b32 v219, v57 offset:51588
	ds_read_u16 v227, v127 offset:19040
	ds_read_b32 v220, v57 offset:51592
	ds_read_u16 v228, v127 offset:19312
	ds_read_b32 v221, v57 offset:51596
	ds_read_u16 v229, v127 offset:19584
	ds_read_b32 v222, v57 offset:51616
	ds_read_u16 v230, v127 offset:20944
	ds_read_b32 v223, v57 offset:51620
	ds_read_u16 v231, v127 offset:21216
	ds_read_b32 v224, v57 offset:51624
	ds_read_u16 v232, v127 offset:21488
	ds_read_b32 v225, v57 offset:51628
	ds_read_u16 v233, v127 offset:21760
	s_waitcnt lgkmcnt(0)
	v_lshlrev_b32_e32 v226, 16, v226
	v_lshlrev_b32_e32 v227, 16, v227
	v_lshlrev_b32_e32 v228, 16, v228
	v_lshlrev_b32_e32 v229, 16, v229
	v_lshlrev_b32_e32 v230, 16, v230
	v_lshlrev_b32_e32 v231, 16, v231
	v_lshlrev_b32_e32 v232, 16, v232
	v_lshlrev_b32_e32 v233, 16, v233
	v_mul_f32_e32 v123, v218, v226
	v_mul_f32_e32 v124, v219, v227
	v_mul_f32_e32 v125, v220, v228
	v_mul_f32_e32 v126, v221, v229
	v_mul_f32_e32 v115, v222, v230
	v_mul_f32_e32 v116, v223, v231
	v_mul_f32_e32 v117, v224, v232
	v_mul_f32_e32 v118, v225, v233
	ds_read_b32 v218, v57 offset:51648
	ds_read_u16 v226, v127 offset:23120
	ds_read_b32 v219, v57 offset:51652
	ds_read_u16 v227, v127 offset:23392
	ds_read_b32 v220, v57 offset:51656
	ds_read_u16 v228, v127 offset:23664
	ds_read_b32 v221, v57 offset:51660
	ds_read_u16 v229, v127 offset:23936
	ds_read_b32 v222, v57 offset:51680
	ds_read_u16 v230, v127 offset:25296
	ds_read_b32 v223, v57 offset:51684
	ds_read_u16 v231, v127 offset:25568
	ds_read_b32 v224, v57 offset:51688
	ds_read_u16 v232, v127 offset:25840
	s_waitcnt lgkmcnt(0)
	v_lshlrev_b32_e32 v226, 16, v226
	v_lshlrev_b32_e32 v227, 16, v227
	v_lshlrev_b32_e32 v228, 16, v228
	v_lshlrev_b32_e32 v229, 16, v229
	v_lshlrev_b32_e32 v230, 16, v230
	v_lshlrev_b32_e32 v231, 16, v231
	v_lshlrev_b32_e32 v232, 16, v232
	v_mul_f32_e32 v15, v218, v226
	v_mul_f32_e32 v14, v219, v227
	v_mul_f32_e32 v13, v220, v228
	v_mul_f32_e32 v12, v221, v229
	v_mul_f32_e32 v3, v222, v230
	v_mul_f32_e32 v2, v223, v231
	v_mul_f32_e32 v1, v224, v232
.Lxi_done:
	s_mov_b64 s[4:5], exec

.LBB0_848:
	v_ashrrev_i32_e32 v24, 1, v4
	v_ashrrev_i32_e32 v25, 31, v24
	v_and_or_b32 v5, v9, 4, v14
	v_lshlrev_b64 v[20:21], 11, v[24:25]
	v_lshl_add_u64 v[16:17], s[44:45], 0, v[20:21]
	v_lshlrev_b32_e32 v128, 8, v5
	v_lshl_add_u64 v[20:21], s[40:41], 0, v[20:21]
	v_lshl_add_u64 v[16:17], v[16:17], 0, v[128:129]
	v_lshlrev_b32_e32 v26, 1, v12
	v_mov_b32_e32 v27, v129
	v_lshl_add_u64 v[20:21], v[20:21], 0, v[128:129]
	v_lshl_add_u64 v[16:17], v[16:17], 0, v[26:27]
	v_lshl_add_u64 v[20:21], v[20:21], 0, v[26:27]
	global_load_dwordx4 v[16:19], v[16:17], off
	v_mov_b64_e32 v[28:29], s[46:47]
	global_load_dwordx4 v[20:23], v[20:21], off
	v_mad_i64_i32 v[28:29], s[30:31], v24, s27, v[28:29]
	v_lshlrev_b64 v[24:25], 12, v[24:25]
	v_lshl_add_u64 v[24:25], s[48:49], 0, v[24:25]
	v_lshl_add_u64 v[28:29], v[28:29], 0, v[128:129]
	v_lshl_add_u64 v[24:25], v[24:25], 0, v[128:129]
	v_lshl_add_u64 v[28:29], v[28:29], 0, v[26:27]
	global_load_dwordx4 v[200:203], v[28:29], off
	v_lshl_add_u64 v[30:31], v[24:25], 0, v[26:27]
	v_add_u32_e32 v4, s34, v4
	v_add_u32_e32 v9, s35, v9
	s_waitcnt vmcnt(2)
	v_lshlrev_b32_e32 v25, 16, v17
	v_lshlrev_b32_e32 v24, 16, v16
	s_waitcnt vmcnt(1)
	v_lshlrev_b32_e32 v27, 16, v21
	v_lshlrev_b32_e32 v26, 16, v20
	v_pk_add_f32 v[32:33], v[24:25], v[26:27]
	v_and_b32_e32 v17, 0xffff0000, v17
	v_and_b32_e32 v16, 0xffff0000, v16
	v_and_b32_e32 v21, 0xffff0000, v21
	v_and_b32_e32 v20, 0xffff0000, v20
	v_pk_add_f32 v[16:17], v[16:17], v[20:21]
	v_mov_b32_e32 v21, v33
	v_mov_b32_e32 v20, v17
	v_pk_mul_f32 v[20:21], v[20:21], v[20:21]
	s_waitcnt vmcnt(0)
	v_mov_b32_e32 v24, v200
	v_mov_b32_e32 v25, v201
	v_mov_b32_e32 v26, v202
	v_mov_b32_e32 v27, v203
	v_lshlrev_b32_e32 v5, 16, v25
	v_lshlrev_b32_e32 v34, 16, v24
	v_mul_f32_e32 v28, 0xbfb8aa3b, v34
	v_and_b32_e32 v35, 0xffff0000, v25
	v_mul_f32_e32 v25, 0xbfb8aa3b, v5
	v_exp_f32_e32 v28, v28
	v_exp_f32_e32 v29, v25
	v_and_b32_e32 v36, 0xffff0000, v24
	v_mul_f32_e32 v24, 0xbfb8aa3b, v36
	v_exp_f32_e32 v24, v24
	v_pk_add_f32 v[28:29], v[28:29], 1.0 op_sel_hi:[1,0]
	v_and_b32_e32 v41, 0xffff0000, v27
	v_div_scale_f32 v25, s[30:31], v29, v29, v5
	v_rcp_f32_e32 v37, v25
	v_and_b32_e32 v42, 0xffff0000, v26
	v_fma_f32 v38, -v25, v37, 1.0
	v_fmac_f32_e32 v37, v38, v37
	v_div_scale_f32 v38, vcc, v5, v29, v5
	v_mul_f32_e32 v39, v38, v37
	v_fma_f32 v40, -v25, v39, v38
	v_fmac_f32_e32 v39, v40, v37
	v_fma_f32 v25, -v25, v39, v38
	v_div_fmas_f32 v25, v25, v37, v39
	v_div_fixup_f32 v29, v25, v29, v5
	v_div_scale_f32 v5, s[30:31], v28, v28, v34
	v_rcp_f32_e32 v25, v5
	v_lshlrev_b32_e32 v40, 16, v26
	v_mul_f32_e32 v26, 0xbfb8aa3b, v42
	v_exp_f32_e32 v26, v26
	v_fma_f32 v37, -v5, v25, 1.0
	v_fmac_f32_e32 v25, v37, v25
	v_div_scale_f32 v37, vcc, v34, v28, v34
	v_mul_f32_e32 v38, v37, v25
	v_fma_f32 v39, -v5, v38, v37
	v_fmac_f32_e32 v38, v39, v25
	v_fma_f32 v5, -v5, v38, v37
	v_div_fmas_f32 v5, v5, v25, v38
	v_div_fixup_f32 v28, v5, v28, v34
	v_mul_f32_e32 v5, 0xbfb8aa3b, v35
	v_exp_f32_e32 v25, v5
	s_nop 0
	v_pk_add_f32 v[24:25], v[24:25], 1.0 op_sel_hi:[1,0]
	s_nop 0
	v_div_scale_f32 v5, s[30:31], v25, v25, v35
	v_rcp_f32_e32 v34, v5
	s_nop 0
	v_fma_f32 v37, -v5, v34, 1.0
	v_fmac_f32_e32 v34, v37, v34
	v_div_scale_f32 v37, vcc, v35, v25, v35
	v_mul_f32_e32 v38, v37, v34
	v_fma_f32 v39, -v5, v38, v37
	v_fmac_f32_e32 v38, v39, v34
	v_fma_f32 v5, -v5, v38, v37
	v_div_fmas_f32 v5, v5, v34, v38
	v_div_fixup_f32 v25, v5, v25, v35
	v_div_scale_f32 v5, s[30:31], v24, v24, v36
	v_rcp_f32_e32 v34, v5
	s_nop 0
	v_fma_f32 v35, -v5, v34, 1.0
	v_fmac_f32_e32 v34, v35, v34
	v_div_scale_f32 v35, vcc, v36, v24, v36
	v_mul_f32_e32 v37, v35, v34
	v_fma_f32 v38, -v5, v37, v35
	v_fmac_f32_e32 v37, v38, v34
	v_fma_f32 v5, -v5, v37, v35
	v_div_fmas_f32 v5, v5, v34, v37
	v_div_fixup_f32 v24, v5, v24, v36
	v_lshlrev_b32_e32 v5, 16, v27
	v_mul_f32_e32 v38, 0xbfb8aa3b, v40
	v_mul_f32_e32 v27, 0xbfb8aa3b, v5
	v_exp_f32_e32 v38, v38
	v_exp_f32_e32 v39, v27
	v_lshlrev_b32_e32 v35, 16, v19
	v_lshlrev_b32_e32 v34, 16, v18
	v_lshlrev_b32_e32 v37, 16, v23
	v_pk_add_f32 v[38:39], v[38:39], 1.0 op_sel_hi:[1,0]
	v_lshlrev_b32_e32 v36, 16, v22
	v_div_scale_f32 v27, s[30:31], v39, v39, v5
	v_rcp_f32_e32 v43, v27
	v_and_b32_e32 v19, 0xffff0000, v19
	v_and_b32_e32 v18, 0xffff0000, v18
	v_and_b32_e32 v23, 0xffff0000, v23
	v_fma_f32 v44, -v27, v43, 1.0
	v_fmac_f32_e32 v43, v44, v43
	v_div_scale_f32 v44, vcc, v5, v39, v5
	v_mul_f32_e32 v45, v44, v43
	v_fma_f32 v46, -v27, v45, v44
	v_fmac_f32_e32 v45, v46, v43
	v_fma_f32 v27, -v27, v45, v44
	v_div_fmas_f32 v27, v27, v43, v45
	v_div_fixup_f32 v39, v27, v39, v5
	v_div_scale_f32 v5, s[30:31], v38, v38, v40
	v_rcp_f32_e32 v27, v5
	v_and_b32_e32 v22, 0xffff0000, v22
	v_pk_add_f32 v[34:35], v[34:35], v[36:37]
	v_pk_add_f32 v[18:19], v[18:19], v[22:23]
	v_fma_f32 v43, -v5, v27, 1.0
	v_fmac_f32_e32 v27, v43, v27
	v_div_scale_f32 v43, vcc, v40, v38, v40
	v_mul_f32_e32 v44, v43, v27
	v_fma_f32 v45, -v5, v44, v43
	v_fmac_f32_e32 v44, v45, v27
	v_fma_f32 v5, -v5, v44, v43
	v_div_fmas_f32 v5, v5, v27, v44
	v_div_fixup_f32 v38, v5, v38, v40
	v_mul_f32_e32 v5, 0xbfb8aa3b, v41
	v_exp_f32_e32 v27, v5
	v_mov_b32_e32 v22, v18
	v_mov_b32_e32 v23, v34
	v_pk_mul_f32 v[22:23], v[22:23], v[22:23]
	v_pk_add_f32 v[26:27], v[26:27], 1.0 op_sel_hi:[1,0]
	v_mov_b32_e32 v36, v19
	v_div_scale_f32 v5, s[30:31], v27, v27, v41
	v_rcp_f32_e32 v40, v5
	v_mov_b32_e32 v37, v35
	v_pk_mul_f32 v[36:37], v[36:37], v[36:37]
	v_fma_f32 v43, -v5, v40, 1.0
	v_fmac_f32_e32 v40, v43, v40
	v_div_scale_f32 v43, vcc, v41, v27, v41
	v_mul_f32_e32 v44, v43, v40
	v_fma_f32 v45, -v5, v44, v43
	v_fmac_f32_e32 v44, v45, v40
	v_fma_f32 v5, -v5, v44, v43
	v_div_fmas_f32 v5, v5, v40, v44
	v_div_fixup_f32 v27, v5, v27, v41
	v_div_scale_f32 v5, s[30:31], v26, v26, v42
	v_rcp_f32_e32 v40, v5
	s_nop 0
	v_fma_f32 v41, -v5, v40, 1.0
	v_fmac_f32_e32 v40, v41, v40
	v_div_scale_f32 v41, vcc, v42, v26, v42
	v_mul_f32_e32 v43, v41, v40
	v_fma_f32 v44, -v5, v43, v41
	v_fmac_f32_e32 v43, v44, v40
	v_fma_f32 v5, -v5, v43, v41
	v_div_fmas_f32 v5, v5, v40, v43
	v_div_fixup_f32 v26, v5, v26, v42
	v_mul_f32_e32 v5, v32, v32
	v_fmac_f32_e32 v5, v16, v16
	v_add_f32_e32 v5, v21, v5
	v_add_f32_e32 v5, v20, v5
	v_add_f32_e32 v5, v23, v5
	v_add_f32_e32 v5, v22, v5
	v_add_f32_e32 v5, v37, v5
	v_add_f32_e32 v5, v36, v5
	s_nop 1
	v_add_f32_dpp v5, v5, v5 quad_perm:[1,0,3,2] row_mask:0xf bank_mask:0xf bound_ctrl:1
	s_nop 1
	v_add_f32_dpp v5, v5, v5 quad_perm:[2,3,0,1] row_mask:0xf bank_mask:0xf bound_ctrl:1
	s_nop 1
	v_add_f32_dpp v5, v5, v5 row_half_mirror row_mask:0xf bank_mask:0xf bound_ctrl:1
	s_nop 1
	v_add_f32_dpp v5, v5, v5 row_mirror row_mask:0xf bank_mask:0xf bound_ctrl:1
	v_fmamk_f32 v5, v5, 0x3c000000, v149
	v_cmp_gt_f32_e32 vcc, s95, v5
	v_mul_f32_e32 v20, 0x4b800000, v5
	s_nop 0
	v_cndmask_b32_e32 v5, v5, v20, vcc
	v_rsq_f32_e32 v5, v5
	s_nop 0
	v_mul_f32_e32 v20, 0x45800000, v5
	v_cndmask_b32_e32 v20, v5, v20, vcc
	v_pk_mul_f32 v[22:23], v[32:33], v[20:21] op_sel_hi:[1,0]
	v_pk_mul_f32 v[16:17], v[16:17], v[20:21] op_sel_hi:[1,0]
	v_pk_mul_f32 v[22:23], v[10:11], v[22:23]
	v_pk_mul_f32 v[16:17], v[2:3], v[16:17]
	v_pk_mul_f32 v[22:23], v[28:29], v[22:23]
	v_pk_mul_f32 v[16:17], v[24:25], v[16:17]
	v_pk_mul_f32 v[24:25], v[34:35], v[20:21] op_sel_hi:[1,0]
	v_pk_mul_f32 v[18:19], v[18:19], v[20:21] op_sel_hi:[1,0]
	v_and_b32_sdwa v20, v22, v150 dst_sel:DWORD dst_unused:UNUSED_PAD src0_sel:WORD_1 src1_sel:DWORD
	v_pk_mul_f32 v[18:19], v[6:7], v[18:19]
	v_add3_u32 v20, v22, v20, s26
	v_and_b32_sdwa v21, v17, v150 dst_sel:DWORD dst_unused:UNUSED_PAD src0_sel:WORD_1 src1_sel:DWORD
	v_and_b32_sdwa v22, v16, v150 dst_sel:DWORD dst_unused:UNUSED_PAD src0_sel:WORD_1 src1_sel:DWORD
	v_pk_mul_f32 v[24:25], v[0:1], v[24:25]
	v_pk_mul_f32 v[18:19], v[26:27], v[18:19]
	v_and_b32_sdwa v5, v23, v150 dst_sel:DWORD dst_unused:UNUSED_PAD src0_sel:WORD_1 src1_sel:DWORD
	v_add3_u32 v17, v17, v21, s26
	v_add3_u32 v16, v16, v22, s26
	v_pk_mul_f32 v[24:25], v[38:39], v[24:25]
	v_add3_u32 v5, v23, v5, s26
	v_and_b32_e32 v17, 0xffff0000, v17
	v_and_b32_e32 v16, 0xffff0000, v16
	v_and_b32_sdwa v21, v19, v150 dst_sel:DWORD dst_unused:UNUSED_PAD src0_sel:WORD_1 src1_sel:DWORD
	v_and_b32_sdwa v22, v18, v150 dst_sel:DWORD dst_unused:UNUSED_PAD src0_sel:WORD_1 src1_sel:DWORD
	v_or_b32_sdwa v17, v17, v5 dst_sel:DWORD dst_unused:UNUSED_PAD src0_sel:DWORD src1_sel:WORD_1
	v_or_b32_sdwa v16, v16, v20 dst_sel:DWORD dst_unused:UNUSED_PAD src0_sel:DWORD src1_sel:WORD_1
	v_and_b32_sdwa v5, v25, v150 dst_sel:DWORD dst_unused:UNUSED_PAD src0_sel:WORD_1 src1_sel:DWORD
	v_and_b32_sdwa v20, v24, v150 dst_sel:DWORD dst_unused:UNUSED_PAD src0_sel:WORD_1 src1_sel:DWORD
	v_add3_u32 v19, v19, v21, s26
	v_add3_u32 v18, v18, v22, s26
	v_add3_u32 v20, v24, v20, s26
	v_add3_u32 v5, v25, v5, s26
	v_and_b32_e32 v19, 0xffff0000, v19
	v_and_b32_e32 v18, 0xffff0000, v18
	v_cmp_lt_i32_e32 vcc, s36, v4
	v_or_b32_sdwa v19, v19, v5 dst_sel:DWORD dst_unused:UNUSED_PAD src0_sel:DWORD src1_sel:WORD_1
	v_or_b32_sdwa v18, v18, v20 dst_sel:DWORD dst_unused:UNUSED_PAD src0_sel:DWORD src1_sel:WORD_1
	s_or_b64 s[42:43], vcc, s[42:43]
	global_store_dwordx4 v[30:31], v[16:19], off
	s_andn2_b64 exec, exec, s[42:43]
	s_cbranch_execnz .LBB0_848

.LBB0_988:
	v_or_b32_e32 v16, v19, v73
	v_lshl_add_u32 v17, v18, 6, 0
	v_lshlrev_b32_e32 v38, 1, v69
	v_mul_u32_u24_e32 v35, 0x90, v16
	v_add3_u32 v16, v17, v38, v35
	s_waitcnt vmcnt(0)
	v_bfe_u32 v17, v1, 16, 1
	v_add3_u32 v17, v1, v17, s26
	ds_write_b16_d16_hi v16, v17 offset:144
	v_bfe_u32 v17, v2, 16, 1
	v_add3_u32 v17, v2, v17, s26
	ds_write_b16_d16_hi v16, v17 offset:288
	v_bfe_u32 v17, v3, 16, 1
	v_add3_u32 v17, v3, v17, s26
	ds_write_b16_d16_hi v16, v17 offset:432
	v_bfe_u32 v17, v4, 16, 1
	v_add3_u32 v17, v4, v17, s26
	ds_write_b16_d16_hi v16, v17 offset:1152
	v_bfe_u32 v17, v5, 16, 1
	v_add3_u32 v17, v5, v17, s26
	ds_write_b16_d16_hi v16, v17 offset:1296
	v_bfe_u32 v17, v6, 16, 1
	v_add3_u32 v17, v6, v17, s26
	ds_write_b16_d16_hi v16, v17 offset:1440
	v_bfe_u32 v17, v7, 16, 1
	v_add3_u32 v17, v7, v17, s26
	s_and_b64 s[36:37], s[4:5], exec
	v_readlane_b32 s35, v252, 15
	ds_write_b16_d16_hi v16, v17 offset:1584
	v_bfe_u32 v17, v8, 16, 1
	s_cselect_b32 s34, s34, s35
	v_add3_u32 v17, v8, v17, s26
	s_lshl_b32 s34, s34, 11
	ds_write_b16_d16_hi v16, v17 offset:2304
	v_bfe_u32 v17, v9, 16, 1
	s_add_i32 s36, s34, 0x1000
	s_lshl_b32 s37, s35, 8
	v_add3_u32 v17, v9, v17, s26
	s_and_b64 s[34:35], s[4:5], exec
	ds_write_b16_d16_hi v16, v17 offset:2448
	v_bfe_u32 v17, v10, 16, 1
	s_cselect_b32 s34, s36, s37
	s_add_u32 s38, s44, 0x15000000
	v_add3_u32 v17, v10, v17, s26
	s_addc_u32 s39, s45, 0
	ds_write_b16_d16_hi v16, v17 offset:2592
	v_bfe_u32 v17, v11, 16, 1
	s_cmp_eq_u32 s7, 0
	v_add3_u32 v17, v11, v17, s26
	s_cselect_b64 vcc, -1, 0
	ds_write_b16_d16_hi v16, v17 offset:2736
	v_bfe_u32 v17, v12, 16, 1
	s_and_b64 s[36:37], vcc, exec
	v_add3_u32 v17, v12, v17, s26
	s_mov_b32 s36, 0x21000000
	ds_write_b16_d16_hi v16, v17 offset:3456
	v_bfe_u32 v17, v13, 16, 1
	s_cselect_b32 s40, s36, 0x22800000
	s_and_b64 s[4:5], s[4:5], exec
	v_add3_u32 v17, v13, v17, s26
	s_movk_i32 s4, 0x800
	ds_write_b16_d16_hi v16, v17 offset:3600
	v_bfe_u32 v17, v14, 16, 1
	s_cselect_b32 s36, s4, 0x100
	v_add3_u32 v17, v14, v17, s26
	s_lshr_b32 s37, s36, 6
	v_bfe_u32 v21, v0, 16, 1
	ds_write_b16_d16_hi v16, v17 offset:3744
	v_bfe_u32 v17, v15, 16, 1
	v_add3_u32 v21, v0, v21, s26
	v_add3_u32 v17, v15, v17, s26
	s_add_u32 s46, s44, s40
	s_movk_i32 s4, 0x100
	ds_write_b16_d16_hi v16, v21
	ds_write_b16_d16_hi v16, v17 offset:3888
	s_addc_u32 s47, s45, 0
	v_cmp_gt_u32_e64 s[40:41], s4, v33
	v_lshlrev_b32_e32 v16, 2, v33
	s_lshl_b32 s4, s7, 6
	v_and_b32_e32 v16, 12, v16
	s_add_u32 s4, s44, s4
	s_addc_u32 s5, s45, 0
	v_lshlrev_b32_e32 v40, 2, v16
	v_mov_b32_e32 v41, v129
	v_lshl_add_u64 v[16:17], s[4:5], 0, v[40:41]
	s_mov_b64 s[4:5], 0x28800000
	v_lshl_add_u64 v[42:43], v[16:17], 0, s[4:5]
	v_readlane_b32 s4, v252, 17
	s_lshl_b32 s7, s4, 7
	s_lshl_b32 s4, s4, 8
	s_add_u32 s4, s46, s4
	s_addc_u32 s5, s47, 0
	v_lshlrev_b32_e32 v128, 1, v73
	v_lshlrev_b32_e32 v78, 4, v20
	v_mul_u32_u24_e32 v81, 0x1200, v20
	v_mul_u32_u24_e32 v84, 0x900, v20
	v_lshl_add_u64 v[20:21], s[4:5], 0, v[128:129]
	s_movk_i32 s4, 0x7f
	v_cmp_lt_u32_e64 s[44:45], s4, v33
	s_movk_i32 s4, 0xbf
	v_cmp_lt_u32_e64 s[46:47], s4, v33
	s_movk_i32 s4, 0xff
	v_lshrrev_b32_e32 v22, 6, v33
	v_mov_b32_e32 v39, v129
	v_cmp_lt_u32_e64 s[48:49], s4, v33
	s_movk_i32 s4, 0x13f
	v_lshlrev_b32_e32 v75, 3, v22
	v_lshl_add_u64 v[44:45], v[20:21], 0, v[38:39]
	v_cmp_lt_u32_e64 s[50:51], s4, v33
	s_movk_i32 s4, 0x17f
	v_mul_u32_u24_e32 v20, 0x240, v22
	v_lshrrev_b32_e32 v37, 2, v33
	v_or_b32_e32 v24, v68, v19
	v_cmp_lt_u32_e64 s[52:53], s4, v33
	v_or_b32_e32 v39, v20, v32
	v_or_b32_e32 v20, 1, v75
	s_movk_i32 s4, 0x48
	v_lshlrev_b32_e32 v74, 9, v22
	v_lshlrev_b32_e32 v77, 4, v22
	v_and_b32_e32 v16, 0x7f, v33
	v_mul_u32_u24_e32 v17, 0x48, v69
	v_and_b32_e32 v23, 8, v37
	v_or_b32_e32 v82, v73, v69
	v_cmp_eq_u32_e64 s[54:55], 7, v22
	v_mad_u32_u24 v85, v20, s4, v32
	v_or_b32_e32 v20, 1, v24
	v_or_b32_e32 v21, 2, v24
	v_or_b32_e32 v22, 3, v24
	v_or_b32_e32 v25, 8, v24
	v_or_b32_e32 v26, 9, v24
	v_or_b32_e32 v27, 10, v24
	v_or_b32_e32 v28, 11, v24
	v_or_b32_e32 v29, 16, v24
	v_or_b32_e32 v30, 17, v24
	v_or_b32_e32 v31, 18, v24
	v_or_b32_e32 v46, 19, v24
	v_or_b32_e32 v47, 24, v24
	v_or_b32_e32 v48, 25, v24
	v_or_b32_e32 v49, 26, v24
	v_or_b32_e32 v50, 27, v24
	s_movk_i32 s4, 0x90
	v_add_u32_e32 v99, v68, v19
	s_mov_b32 s35, 0
	v_lshlrev_b32_e32 v41, 6, v37
	v_cmp_gt_u32_e64 s[42:43], 64, v33
	v_mul_u32_u24_e32 v76, 0x90, v32
	v_mul_u32_u24_e32 v79, 0x90, v16
	v_mul_u32_u24_e32 v80, 0x1200, v18
	v_mul_u32_u24_e32 v83, 0x900, v18
	v_add_u32_e32 v86, 0x48, v85
	v_add_u32_e32 v87, 0x90, v85
	v_add_u32_e32 v88, 0xd8, v85
	v_add_u32_e32 v89, 0x120, v85
	v_add_u32_e32 v90, 0x168, v85
	v_add_u32_e32 v91, 0x1b0, v85
	v_cmp_gt_u32_e64 s[56:57], v82, v24
	v_mul_u32_u24_e32 v92, 0x90, v24
	v_cmp_gt_u32_e64 s[58:59], v82, v20
	v_cmp_gt_u32_e64 s[60:61], v82, v21
	v_cmp_gt_u32_e64 s[62:63], v82, v22
	v_cmp_gt_u32_e64 s[64:65], v82, v25
	v_mad_u32_u24 v93, v24, s4, v163
	v_cmp_gt_u32_e64 s[66:67], v82, v26
	v_cmp_gt_u32_e64 s[68:69], v82, v27
	v_cmp_gt_u32_e64 s[70:71], v82, v28
	v_cmp_gt_u32_e64 s[72:73], v82, v29
	v_mad_u32_u24 v94, v24, s4, v161
	v_cmp_gt_u32_e64 s[74:75], v82, v30
	v_cmp_gt_u32_e64 s[76:77], v82, v31
	v_cmp_gt_u32_e64 s[78:79], v82, v46
	v_cmp_gt_u32_e64 s[80:81], v82, v47
	v_mad_u32_u24 v95, v24, s4, v164
	v_cmp_gt_u32_e64 s[82:83], v82, v48
	v_cmp_gt_u32_e64 s[84:85], v82, v49
	v_cmp_gt_u32_e64 s[86:87], v82, v50
	v_mul_i32_i24_e32 v96, 0xffffee40, v18
	v_not_b32_e32 v97, v37
	v_not_b32_e32 v98, v78
	v_sub_u32_e32 v100, 0, v99
	v_sub_u32_e32 v101, 0, v75
	s_lshl_b32 s88, s6, 1
	v_lshlrev_b32_e32 v128, 1, v32
	s_lshl_b32 s4, s7, 1
	v_lshlrev_b32_e32 v46, 1, v16
	v_lshlrev_b32_e32 v102, 1, v17
	v_lshlrev_b32_e32 v103, 1, v23
	s_mov_b32 s6, s36
	s_mov_b32 s7, 0
	s_and_saveexec_b64 s[90:91], s[40:41]
	v_add_u32_e32 v204, s35, v37
	v_add_u32_e32 v205, s6, v97
	v_cndmask_b32_e32 v204, v205, v204, vcc
	v_add_u32_e32 v204, s34, v204
	v_ashrrev_i32_e32 v205, 31, v204
	v_lshlrev_b64 v[204:205], 7, v[204:205]
	v_lshl_add_u64 v[204:205], v[42:43], 0, v[204:205]
	global_load_dwordx4 v[206:209], v[204:205], off
	s_or_b64 exec, exec, s[90:91]
	s_branch .LBB0_990
.LBB0_989:
	s_or_b64 exec, exec, s[90:91]
	v_lshl_add_u32 v47, v83, 1, v105
	v_lshl_add_u32 v16, v84, 1, v105
	v_add3_u32 v50, v47, v102, v103
	v_add3_u32 v51, v16, v102, v103
	ds_read_b128 v[16:19], v50 offset:18432
	ds_read_b128 v[20:23], v51
	ds_read_b128 v[106:109], v50 offset:18464
	ds_read_b128 v[110:113], v51 offset:32
	ds_read_b128 v[114:117], v50 offset:18496
	ds_read_b128 v[118:121], v51 offset:64
	ds_read_b128 v[122:125], v50 offset:18528
	ds_read_b128 v[130:133], v51 offset:96
	s_waitcnt lgkmcnt(6)
	v_mfma_f32_32x32x16_bf16 v[16:31], v[16:19], v[20:23], 0
	s_waitcnt lgkmcnt(0)
	s_barrier
	v_lshl_add_u64 v[48:49], v[48:49], 1, v[44:45]
	s_add_i32 s7, s7, 1
	v_mfma_f32_32x32x16_bf16 v[16:31], v[106:109], v[110:113], v[16:31]
	v_mfma_f32_32x32x16_bf16 v[16:31], v[114:117], v[118:121], v[16:31]
	v_mfma_f32_32x32x16_bf16 v[16:31], v[122:125], v[130:133], v[16:31]
	ds_read_b128 v[106:109], v50 offset:64512
	ds_read_b128 v[114:117], v51 offset:46080
	ds_read_b128 v[110:113], v50 offset:64544
	ds_read_b128 v[118:121], v51 offset:46112
	ds_read_b128 v[122:125], v50 offset:64576
	ds_read_b128 v[130:133], v51 offset:46144
	ds_read_b128 v[134:137], v50 offset:64608
	ds_read_b128 v[138:141], v51 offset:46176
	s_waitcnt lgkmcnt(6)
	v_mfma_f32_32x32x16_bf16 v[16:31], v[106:109], v[114:117], v[16:31]
	s_waitcnt lgkmcnt(4)
	v_mfma_f32_32x32x16_bf16 v[16:31], v[110:113], v[118:121], v[16:31]
	s_waitcnt lgkmcnt(2)
	v_mfma_f32_32x32x16_bf16 v[16:31], v[122:125], v[130:133], v[16:31]
	s_waitcnt lgkmcnt(0)
	v_mfma_f32_32x32x16_bf16 v[16:31], v[134:137], v[138:141], v[16:31]
	ds_read_b128 v[108:111], v50 offset:36928
	ds_read_b128 v[112:115], v51 offset:46176
	s_nop 9
	v_bfe_u32 v52, v16, 16, 1
	v_add3_u32 v53, v16, v52, s26
	v_add_u32_e32 v52, s6, v100
	v_add_u32_e32 v16, s35, v99
	v_add_u32_e32 v105, -1, v52
	v_cndmask_b32_e32 v105, v105, v16, vcc
	v_add_u32_e32 v106, s34, v105
	v_ashrrev_i32_e32 v107, 31, v106
	v_lshlrev_b64 v[106:107], 11, v[106:107]
	v_lshl_add_u64 v[106:107], v[48:49], 0, v[106:107]
	global_store_short_d16_hi v[106:107], v53, off
	v_bfe_u32 v53, v17, 16, 1
	v_add3_u32 v17, v17, v53, s26
	v_add_u32_e32 v53, 1, v16
	v_add_u32_e32 v105, -2, v52
	v_cndmask_b32_e32 v53, v105, v53, vcc
	v_add_u32_e32 v106, s34, v53
	v_ashrrev_i32_e32 v107, 31, v106
	v_lshlrev_b64 v[106:107], 11, v[106:107]
	v_lshl_add_u64 v[106:107], v[48:49], 0, v[106:107]
	global_store_short_d16_hi v[106:107], v17, off
	v_bfe_u32 v17, v18, 16, 1
	v_add3_u32 v17, v18, v17, s26
	v_add_u32_e32 v18, 2, v16
	v_add_u32_e32 v53, -3, v52
	v_cndmask_b32_e32 v18, v53, v18, vcc
	v_add_u32_e32 v106, s34, v18
	v_ashrrev_i32_e32 v107, 31, v106
	v_lshlrev_b64 v[106:107], 11, v[106:107]
	v_lshl_add_u64 v[106:107], v[48:49], 0, v[106:107]
	global_store_short_d16_hi v[106:107], v17, off
	v_bfe_u32 v17, v19, 16, 1
	v_add3_u32 v17, v19, v17, s26
	v_add_u32_e32 v18, 3, v16
	v_add_u32_e32 v19, -4, v52
	v_cndmask_b32_e32 v18, v19, v18, vcc
	v_add_u32_e32 v18, s34, v18
	v_ashrrev_i32_e32 v19, 31, v18
	v_lshlrev_b64 v[18:19], 11, v[18:19]
	v_lshl_add_u64 v[18:19], v[48:49], 0, v[18:19]
	global_store_short_d16_hi v[18:19], v17, off
	v_add_u32_e32 v18, 8, v16
	v_add_u32_e32 v19, -9, v52
	v_cndmask_b32_e32 v18, v19, v18, vcc
	v_add_u32_e32 v18, s34, v18
	v_ashrrev_i32_e32 v19, 31, v18
	v_bfe_u32 v17, v20, 16, 1
	v_lshlrev_b64 v[18:19], 11, v[18:19]
	v_add3_u32 v17, v20, v17, s26
	v_lshl_add_u64 v[18:19], v[48:49], 0, v[18:19]
	global_store_short_d16_hi v[18:19], v17, off
	v_add_u32_e32 v18, 9, v16
	v_add_u32_e32 v19, -10, v52
	v_cndmask_b32_e32 v18, v19, v18, vcc
	v_add_u32_e32 v18, s34, v18
	v_ashrrev_i32_e32 v19, 31, v18
	v_bfe_u32 v17, v21, 16, 1
	v_lshlrev_b64 v[18:19], 11, v[18:19]
	v_add3_u32 v17, v21, v17, s26
	v_lshl_add_u64 v[18:19], v[48:49], 0, v[18:19]
	global_store_short_d16_hi v[18:19], v17, off
	v_add_u32_e32 v18, 10, v16
	v_add_u32_e32 v19, -11, v52
	v_cndmask_b32_e32 v18, v19, v18, vcc
	v_add_u32_e32 v18, s34, v18
	v_ashrrev_i32_e32 v19, 31, v18
	v_bfe_u32 v17, v22, 16, 1
	v_lshlrev_b64 v[18:19], 11, v[18:19]
	v_add3_u32 v17, v22, v17, s26
	v_lshl_add_u64 v[18:19], v[48:49], 0, v[18:19]
	global_store_short_d16_hi v[18:19], v17, off
	v_add_u32_e32 v18, 11, v16
	v_add_u32_e32 v19, -12, v52
	v_cndmask_b32_e32 v18, v19, v18, vcc
	v_add_u32_e32 v18, s34, v18
	v_ashrrev_i32_e32 v19, 31, v18
	v_bfe_u32 v17, v23, 16, 1
	v_lshlrev_b64 v[18:19], 11, v[18:19]
	v_add3_u32 v17, v23, v17, s26
	v_lshl_add_u64 v[18:19], v[48:49], 0, v[18:19]
	global_store_short_d16_hi v[18:19], v17, off
	v_add_u32_e32 v18, 16, v16
	v_subrev_u32_e32 v19, 17, v52
	v_cndmask_b32_e32 v18, v19, v18, vcc
	v_add_u32_e32 v18, s34, v18
	v_ashrrev_i32_e32 v19, 31, v18
	v_bfe_u32 v17, v24, 16, 1
	v_lshlrev_b64 v[18:19], 11, v[18:19]
	v_add3_u32 v17, v24, v17, s26
	v_lshl_add_u64 v[18:19], v[48:49], 0, v[18:19]
	global_store_short_d16_hi v[18:19], v17, off
	v_add_u32_e32 v18, 17, v16
	v_subrev_u32_e32 v19, 18, v52
	v_cndmask_b32_e32 v18, v19, v18, vcc
	v_add_u32_e32 v18, s34, v18
	v_ashrrev_i32_e32 v19, 31, v18
	v_bfe_u32 v17, v25, 16, 1
	v_lshlrev_b64 v[18:19], 11, v[18:19]
	v_add3_u32 v17, v25, v17, s26
	v_lshl_add_u64 v[18:19], v[48:49], 0, v[18:19]
	global_store_short_d16_hi v[18:19], v17, off
	v_add_u32_e32 v18, 18, v16
	v_subrev_u32_e32 v19, 19, v52
	v_cndmask_b32_e32 v18, v19, v18, vcc
	v_add_u32_e32 v18, s34, v18
	v_ashrrev_i32_e32 v19, 31, v18
	v_bfe_u32 v17, v26, 16, 1
	v_lshlrev_b64 v[18:19], 11, v[18:19]
	v_add3_u32 v17, v26, v17, s26
	v_lshl_add_u64 v[18:19], v[48:49], 0, v[18:19]
	global_store_short_d16_hi v[18:19], v17, off
	v_add_u32_e32 v18, 19, v16
	v_subrev_u32_e32 v19, 20, v52
	v_cndmask_b32_e32 v18, v19, v18, vcc
	v_add_u32_e32 v18, s34, v18
	v_ashrrev_i32_e32 v19, 31, v18
	v_bfe_u32 v17, v27, 16, 1
	v_lshlrev_b64 v[18:19], 11, v[18:19]
	v_add3_u32 v17, v27, v17, s26
	v_lshl_add_u64 v[18:19], v[48:49], 0, v[18:19]
	global_store_short_d16_hi v[18:19], v17, off
	v_add_u32_e32 v18, 24, v16
	v_subrev_u32_e32 v19, 25, v52
	v_cndmask_b32_e32 v18, v19, v18, vcc
	v_add_u32_e32 v18, s34, v18
	v_ashrrev_i32_e32 v19, 31, v18
	v_bfe_u32 v17, v28, 16, 1
	v_lshlrev_b64 v[18:19], 11, v[18:19]
	v_add3_u32 v17, v28, v17, s26
	v_lshl_add_u64 v[18:19], v[48:49], 0, v[18:19]
	global_store_short_d16_hi v[18:19], v17, off
	v_add_u32_e32 v18, 25, v16
	v_subrev_u32_e32 v19, 26, v52
	v_cndmask_b32_e32 v18, v19, v18, vcc
	v_add_u32_e32 v18, s34, v18
	v_ashrrev_i32_e32 v19, 31, v18
	v_bfe_u32 v17, v29, 16, 1
	v_lshlrev_b64 v[18:19], 11, v[18:19]
	v_add3_u32 v17, v29, v17, s26
	v_lshl_add_u64 v[18:19], v[48:49], 0, v[18:19]
	global_store_short_d16_hi v[18:19], v17, off
	v_add_u32_e32 v18, 26, v16
	v_subrev_u32_e32 v19, 27, v52
	v_cndmask_b32_e32 v18, v19, v18, vcc
	v_add_u32_e32 v18, s34, v18
	v_ashrrev_i32_e32 v19, 31, v18
	v_bfe_u32 v17, v30, 16, 1
	v_lshlrev_b64 v[18:19], 11, v[18:19]
	v_add3_u32 v17, v30, v17, s26
	v_lshl_add_u64 v[18:19], v[48:49], 0, v[18:19]
	global_store_short_d16_hi v[18:19], v17, off
	v_bfe_u32 v17, v31, 16, 1
	v_add3_u32 v18, v31, v17, s26
	v_add_u32_e32 v16, 27, v16
	v_subrev_u32_e32 v17, 28, v52
	v_cndmask_b32_e32 v16, v17, v16, vcc
	v_add_u32_e32 v16, s34, v16
	v_ashrrev_i32_e32 v17, 31, v16
	v_lshlrev_b64 v[16:17], 11, v[16:17]
	v_lshl_add_u64 v[16:17], v[48:49], 0, v[16:17]
	global_store_short_d16_hi v[16:17], v18, off
	v_lshlrev_b32_e32 v16, 2, v68
	v_lshlrev_b32_e32 v17, 2, v69
	v_add3_u32 v16, v104, v16, v17
	ds_read_b32 v16, v16
	ds_read_b128 v[24:27], v50 offset:36864
	ds_read_b128 v[20:23], v51 offset:46112
	ds_read_b128 v[28:31], v50 offset:36896
	ds_read_b128 v[104:107], v51 offset:46144
	s_waitcnt lgkmcnt(4)
	v_mul_f32_e32 v16, 0x3fb8aa3b, v16
	v_exp_f32_e32 v16, v16
	s_add_i32 s35, s35, 64
	s_sub_i32 s6, s6, 64
	s_and_saveexec_b64 s[90:91], s[40:41]
	v_add_u32_e32 v204, s35, v37
	v_add_u32_e32 v205, s6, v97
	v_cndmask_b32_e32 v204, v205, v204, vcc
	v_add_u32_e32 v204, s34, v204
	v_ashrrev_i32_e32 v205, 31, v204
	v_lshlrev_b64 v[204:205], 7, v[204:205]
	v_lshl_add_u64 v[204:205], v[42:43], 0, v[204:205]
	global_load_dwordx4 v[206:209], v[204:205], off
	s_or_b64 exec, exec, s[90:91]
	s_cmp_eq_u32 s37, s7
	v_pk_mul_f32 v[14:15], v[14:15], v[16:17] op_sel_hi:[1,0]
	v_pk_mul_f32 v[12:13], v[12:13], v[16:17] op_sel_hi:[1,0]
	v_pk_mul_f32 v[10:11], v[10:11], v[16:17] op_sel_hi:[1,0]
	v_pk_mul_f32 v[8:9], v[8:9], v[16:17] op_sel_hi:[1,0]
	v_pk_mul_f32 v[6:7], v[6:7], v[16:17] op_sel_hi:[1,0]
	v_pk_mul_f32 v[4:5], v[4:5], v[16:17] op_sel_hi:[1,0]
	v_pk_mul_f32 v[2:3], v[2:3], v[16:17] op_sel_hi:[1,0]
	v_pk_mul_f32 v[0:1], v[0:1], v[16:17] op_sel_hi:[1,0]
	ds_read_b128 v[16:19], v51 offset:46080
	ds_read_b128 v[48:51], v50 offset:36960
	s_waitcnt lgkmcnt(1)
	v_mfma_f32_32x32x16_bf16 v[0:15], v[16:19], v[24:27], v[0:15]
	v_add_u32_e32 v16, v47, v96
	v_add3_u32 v16, v16, v38, v35
	s_waitcnt lgkmcnt(0)
	s_barrier
	v_mfma_f32_32x32x16_bf16 v[0:15], v[20:23], v[28:31], v[0:15]
	v_mfma_f32_32x32x16_bf16 v[0:15], v[104:107], v[108:111], v[0:15]
	v_mfma_f32_32x32x16_bf16 v[0:15], v[112:115], v[48:51], v[0:15]
	s_nop 11
	v_bfe_u32 v17, v0, 16, 1
	v_add3_u32 v17, v0, v17, s26
	ds_write_b16_d16_hi v16, v17
	v_bfe_u32 v17, v1, 16, 1
	v_add3_u32 v17, v1, v17, s26
	ds_write_b16_d16_hi v16, v17 offset:144
	v_bfe_u32 v17, v2, 16, 1
	v_add3_u32 v17, v2, v17, s26
	ds_write_b16_d16_hi v16, v17 offset:288
	v_bfe_u32 v17, v3, 16, 1
	v_add3_u32 v17, v3, v17, s26
	ds_write_b16_d16_hi v16, v17 offset:432
	v_bfe_u32 v17, v4, 16, 1
	v_add3_u32 v17, v4, v17, s26
	ds_write_b16_d16_hi v16, v17 offset:1152
	v_bfe_u32 v17, v5, 16, 1
	v_add3_u32 v17, v5, v17, s26
	ds_write_b16_d16_hi v16, v17 offset:1296
	v_bfe_u32 v17, v6, 16, 1
	v_add3_u32 v17, v6, v17, s26
	ds_write_b16_d16_hi v16, v17 offset:1440
	v_bfe_u32 v17, v7, 16, 1
	v_add3_u32 v17, v7, v17, s26
	ds_write_b16_d16_hi v16, v17 offset:1584
	v_bfe_u32 v17, v8, 16, 1
	v_add3_u32 v17, v8, v17, s26
	ds_write_b16_d16_hi v16, v17 offset:2304
	v_bfe_u32 v17, v9, 16, 1
	v_add3_u32 v17, v9, v17, s26
	ds_write_b16_d16_hi v16, v17 offset:2448
	v_bfe_u32 v17, v10, 16, 1
	v_add3_u32 v17, v10, v17, s26
	ds_write_b16_d16_hi v16, v17 offset:2592
	v_bfe_u32 v17, v11, 16, 1
	v_add3_u32 v17, v11, v17, s26
	ds_write_b16_d16_hi v16, v17 offset:2736
	v_bfe_u32 v17, v12, 16, 1
	v_add3_u32 v17, v12, v17, s26
	ds_write_b16_d16_hi v16, v17 offset:3456
	v_bfe_u32 v17, v13, 16, 1
	v_add3_u32 v17, v13, v17, s26
	ds_write_b16_d16_hi v16, v17 offset:3600
	v_bfe_u32 v17, v14, 16, 1
	v_add3_u32 v17, v14, v17, s26
	ds_write_b16_d16_hi v16, v17 offset:3744
	v_bfe_u32 v17, v15, 16, 1
	v_add3_u32 v17, v15, v17, s26
	ds_write_b16_d16_hi v16, v17 offset:3888
	s_cbranch_scc1 .LBB0_996
.LBB0_990:
	v_mov_b32_e32 v16, s7
	v_mov_b32 v48, 0
	s_nop 0
	v_add_u32_e32 v105, 0, v48
	v_add_u32_e32 v17, 0x12000, v105
	s_and_saveexec_b64 s[90:91], s[40:41]
	s_cbranch_execz .LBB0_992
	v_add3_u32 v16, v17, v41, v40
	s_waitcnt vmcnt(0)
	ds_write_b128 v16, v[206:209]

.LBB0_1052:
	v_ashrrev_i32_e32 v26, 1, v4
	v_ashrrev_i32_e32 v27, 31, v26
	v_and_or_b32 v5, v16, 4, v15
	v_lshlrev_b64 v[22:23], 11, v[26:27]
	v_lshl_add_u64 v[18:19], s[44:45], 0, v[22:23]
	v_lshlrev_b32_e32 v128, 8, v5
	v_lshl_add_u64 v[22:23], s[40:41], 0, v[22:23]
	v_lshl_add_u64 v[18:19], v[18:19], 0, v[128:129]
	v_lshlrev_b32_e32 v28, 1, v12
	v_mov_b32_e32 v29, v129
	v_lshl_add_u64 v[22:23], v[22:23], 0, v[128:129]
	v_lshl_add_u64 v[18:19], v[18:19], 0, v[28:29]
	v_lshl_add_u64 v[22:23], v[22:23], 0, v[28:29]
	global_load_dwordx4 v[18:21], v[18:19], off
	v_mov_b64_e32 v[30:31], s[48:49]
	global_load_dwordx4 v[22:25], v[22:23], off
	v_mad_i64_i32 v[30:31], s[30:31], v26, s0, v[30:31]
	v_lshlrev_b64 v[26:27], 12, v[26:27]
	v_lshl_add_u64 v[26:27], s[46:47], 0, v[26:27]
	v_lshl_add_u64 v[30:31], v[30:31], 0, v[128:129]
	v_lshl_add_u64 v[26:27], v[26:27], 0, v[128:129]
	v_lshl_add_u64 v[30:31], v[30:31], 0, v[28:29]
	global_load_dwordx4 v[200:203], v[30:31], off
	v_lshl_add_u64 v[32:33], v[26:27], 0, v[28:29]
	v_add_u32_e32 v4, s34, v4
	v_add_u32_e32 v16, s35, v16
	s_waitcnt vmcnt(2)
	v_lshlrev_b32_e32 v27, 16, v19
	v_lshlrev_b32_e32 v26, 16, v18
	s_waitcnt vmcnt(1)
	v_lshlrev_b32_e32 v29, 16, v23
	v_lshlrev_b32_e32 v28, 16, v22
	v_pk_add_f32 v[34:35], v[26:27], v[28:29]
	v_and_b32_e32 v19, 0xffff0000, v19
	v_and_b32_e32 v18, 0xffff0000, v18
	v_and_b32_e32 v23, 0xffff0000, v23
	v_and_b32_e32 v22, 0xffff0000, v22
	v_pk_add_f32 v[18:19], v[18:19], v[22:23]
	v_mov_b32_e32 v23, v35
	v_mov_b32_e32 v22, v19
	v_pk_mul_f32 v[22:23], v[22:23], v[22:23]
	s_waitcnt vmcnt(0)
	v_mov_b32_e32 v26, v200
	v_mov_b32_e32 v27, v201
	v_mov_b32_e32 v28, v202
	v_mov_b32_e32 v29, v203
	v_lshlrev_b32_e32 v5, 16, v27
	v_lshlrev_b32_e32 v17, 16, v26
	v_mul_f32_e32 v30, 0xbfb8aa3b, v17
	v_and_b32_e32 v36, 0xffff0000, v27
	v_mul_f32_e32 v27, 0xbfb8aa3b, v5
	v_exp_f32_e32 v30, v30
	v_exp_f32_e32 v31, v27
	v_and_b32_e32 v37, 0xffff0000, v26
	v_mul_f32_e32 v26, 0xbfb8aa3b, v37
	v_exp_f32_e32 v26, v26
	v_pk_add_f32 v[30:31], v[30:31], 1.0 op_sel_hi:[1,0]
	v_and_b32_e32 v42, 0xffff0000, v29
	v_div_scale_f32 v27, s[30:31], v31, v31, v5
	v_rcp_f32_e32 v38, v27
	v_and_b32_e32 v43, 0xffff0000, v28
	v_fma_f32 v39, -v27, v38, 1.0
	v_fmac_f32_e32 v38, v39, v38
	v_div_scale_f32 v39, vcc, v5, v31, v5
	v_mul_f32_e32 v40, v39, v38
	v_fma_f32 v41, -v27, v40, v39
	v_fmac_f32_e32 v40, v41, v38
	v_fma_f32 v27, -v27, v40, v39
	v_div_fmas_f32 v27, v27, v38, v40
	v_div_fixup_f32 v31, v27, v31, v5
	v_div_scale_f32 v5, s[30:31], v30, v30, v17
	v_rcp_f32_e32 v27, v5
	s_nop 0
	v_fma_f32 v38, -v5, v27, 1.0
	v_fmac_f32_e32 v27, v38, v27
	v_div_scale_f32 v38, vcc, v17, v30, v17
	v_mul_f32_e32 v39, v38, v27
	v_fma_f32 v40, -v5, v39, v38
	v_fmac_f32_e32 v39, v40, v27
	v_fma_f32 v5, -v5, v39, v38
	v_div_fmas_f32 v5, v5, v27, v39
	v_div_fixup_f32 v30, v5, v30, v17
	v_mul_f32_e32 v5, 0xbfb8aa3b, v36
	v_exp_f32_e32 v27, v5
	s_nop 0
	v_pk_add_f32 v[26:27], v[26:27], 1.0 op_sel_hi:[1,0]
	s_nop 0
	v_div_scale_f32 v5, s[30:31], v27, v27, v36
	v_rcp_f32_e32 v17, v5
	s_nop 0
	v_fma_f32 v38, -v5, v17, 1.0
	v_fmac_f32_e32 v17, v38, v17
	v_div_scale_f32 v38, vcc, v36, v27, v36
	v_mul_f32_e32 v39, v38, v17
	v_fma_f32 v40, -v5, v39, v38
	v_fmac_f32_e32 v39, v40, v17
	v_fma_f32 v5, -v5, v39, v38
	v_div_fmas_f32 v5, v5, v17, v39
	v_div_fixup_f32 v27, v5, v27, v36
	v_div_scale_f32 v5, s[30:31], v26, v26, v37
	v_rcp_f32_e32 v17, v5
	s_nop 0
	v_fma_f32 v36, -v5, v17, 1.0
	v_fmac_f32_e32 v17, v36, v17
	v_div_scale_f32 v36, vcc, v37, v26, v37
	v_mul_f32_e32 v38, v36, v17
	v_fma_f32 v39, -v5, v38, v36
	v_fmac_f32_e32 v38, v39, v17
	v_fma_f32 v5, -v5, v38, v36
	v_div_fmas_f32 v5, v5, v17, v38
	v_div_fixup_f32 v26, v5, v26, v37
	v_lshlrev_b32_e32 v5, 16, v29
	v_lshlrev_b32_e32 v17, 16, v28
	v_mul_f32_e32 v40, 0xbfb8aa3b, v17
	v_mul_f32_e32 v29, 0xbfb8aa3b, v5
	v_exp_f32_e32 v40, v40
	v_exp_f32_e32 v41, v29
	v_mul_f32_e32 v28, 0xbfb8aa3b, v43
	v_exp_f32_e32 v28, v28
	v_lshlrev_b32_e32 v37, 16, v21
	v_pk_add_f32 v[40:41], v[40:41], 1.0 op_sel_hi:[1,0]
	v_lshlrev_b32_e32 v36, 16, v20
	v_div_scale_f32 v29, s[30:31], v41, v41, v5
	v_rcp_f32_e32 v44, v29
	v_lshlrev_b32_e32 v39, 16, v25
	v_lshlrev_b32_e32 v38, 16, v24
	v_and_b32_e32 v21, 0xffff0000, v21
	v_fma_f32 v45, -v29, v44, 1.0
	v_fmac_f32_e32 v44, v45, v44
	v_div_scale_f32 v45, vcc, v5, v41, v5
	v_mul_f32_e32 v46, v45, v44
	v_fma_f32 v47, -v29, v46, v45
	v_fmac_f32_e32 v46, v47, v44
	v_fma_f32 v29, -v29, v46, v45
	v_div_fmas_f32 v29, v29, v44, v46
	v_div_fixup_f32 v41, v29, v41, v5
	v_div_scale_f32 v5, s[30:31], v40, v40, v17
	v_rcp_f32_e32 v29, v5
	v_and_b32_e32 v20, 0xffff0000, v20
	v_and_b32_e32 v25, 0xffff0000, v25
	v_and_b32_e32 v24, 0xffff0000, v24
	v_fma_f32 v44, -v5, v29, 1.0
	v_fmac_f32_e32 v29, v44, v29
	v_div_scale_f32 v44, vcc, v17, v40, v17
	v_mul_f32_e32 v45, v44, v29
	v_fma_f32 v46, -v5, v45, v44
	v_fmac_f32_e32 v45, v46, v29
	v_fma_f32 v5, -v5, v45, v44
	v_div_fmas_f32 v5, v5, v29, v45
	v_div_fixup_f32 v40, v5, v40, v17
	v_mul_f32_e32 v5, 0xbfb8aa3b, v42
	v_exp_f32_e32 v29, v5
	v_pk_add_f32 v[36:37], v[36:37], v[38:39]
	v_pk_add_f32 v[20:21], v[20:21], v[24:25]
	v_mov_b32_e32 v25, v36
	v_pk_add_f32 v[28:29], v[28:29], 1.0 op_sel_hi:[1,0]
	v_mov_b32_e32 v24, v20
	v_div_scale_f32 v5, s[30:31], v29, v29, v42
	v_rcp_f32_e32 v17, v5
	v_pk_mul_f32 v[24:25], v[24:25], v[24:25]
	v_mov_b32_e32 v38, v21
	v_mov_b32_e32 v39, v37
	v_fma_f32 v44, -v5, v17, 1.0
	v_fmac_f32_e32 v17, v44, v17
	v_div_scale_f32 v44, vcc, v42, v29, v42
	v_mul_f32_e32 v45, v44, v17
	v_fma_f32 v46, -v5, v45, v44
	v_fmac_f32_e32 v45, v46, v17
	v_fma_f32 v5, -v5, v45, v44
	v_div_fmas_f32 v5, v5, v17, v45
	v_div_fixup_f32 v29, v5, v29, v42
	v_div_scale_f32 v5, s[30:31], v28, v28, v43
	v_rcp_f32_e32 v17, v5
	v_pk_mul_f32 v[38:39], v[38:39], v[38:39]
	v_fma_f32 v42, -v5, v17, 1.0
	v_fmac_f32_e32 v17, v42, v17
	v_div_scale_f32 v42, vcc, v43, v28, v43
	v_mul_f32_e32 v44, v42, v17
	v_fma_f32 v45, -v5, v44, v42
	v_fmac_f32_e32 v44, v45, v17
	v_fma_f32 v5, -v5, v44, v42
	v_div_fmas_f32 v5, v5, v17, v44
	v_div_fixup_f32 v28, v5, v28, v43
	v_mul_f32_e32 v5, v34, v34
	v_fmac_f32_e32 v5, v18, v18
	v_add_f32_e32 v5, v23, v5
	v_add_f32_e32 v5, v22, v5
	v_add_f32_e32 v5, v25, v5
	v_add_f32_e32 v5, v24, v5
	v_add_f32_e32 v5, v39, v5
	v_add_f32_e32 v5, v38, v5
	s_nop 1
	v_add_f32_dpp v5, v5, v5 quad_perm:[1,0,3,2] row_mask:0xf bank_mask:0xf bound_ctrl:1
	s_nop 1
	v_add_f32_dpp v5, v5, v5 quad_perm:[2,3,0,1] row_mask:0xf bank_mask:0xf bound_ctrl:1
	s_nop 1
	v_add_f32_dpp v5, v5, v5 row_half_mirror row_mask:0xf bank_mask:0xf bound_ctrl:1
	s_nop 1
	v_add_f32_dpp v5, v5, v5 row_mirror row_mask:0xf bank_mask:0xf bound_ctrl:1
	v_fmamk_f32 v5, v5, 0x3c000000, v149
	v_cmp_gt_f32_e32 vcc, s95, v5
	v_mul_f32_e32 v17, 0x4b800000, v5
	s_nop 0
	v_cndmask_b32_e32 v5, v5, v17, vcc
	v_rsq_f32_e32 v5, v5
	s_nop 0
	v_mul_f32_e32 v17, 0x45800000, v5
	v_cndmask_b32_e32 v22, v5, v17, vcc
	v_pk_mul_f32 v[18:19], v[18:19], v[22:23] op_sel_hi:[1,0]
	v_pk_mul_f32 v[24:25], v[34:35], v[22:23] op_sel_hi:[1,0]
	v_pk_mul_f32 v[18:19], v[2:3], v[18:19]
	v_pk_mul_f32 v[24:25], v[10:11], v[24:25]
	v_pk_mul_f32 v[18:19], v[26:27], v[18:19]
	v_pk_mul_f32 v[20:21], v[20:21], v[22:23] op_sel_hi:[1,0]
	v_pk_mul_f32 v[24:25], v[30:31], v[24:25]
	v_pk_mul_f32 v[26:27], v[36:37], v[22:23] op_sel_hi:[1,0]
	v_pk_mul_f32 v[20:21], v[6:7], v[20:21]
	v_and_b32_sdwa v22, v19, v150 dst_sel:DWORD dst_unused:UNUSED_PAD src0_sel:WORD_1 src1_sel:DWORD
	v_and_b32_sdwa v23, v18, v150 dst_sel:DWORD dst_unused:UNUSED_PAD src0_sel:WORD_1 src1_sel:DWORD
	v_pk_mul_f32 v[26:27], v[0:1], v[26:27]
	v_pk_mul_f32 v[20:21], v[28:29], v[20:21]
	v_and_b32_sdwa v5, v25, v150 dst_sel:DWORD dst_unused:UNUSED_PAD src0_sel:WORD_1 src1_sel:DWORD
	v_and_b32_sdwa v17, v24, v150 dst_sel:DWORD dst_unused:UNUSED_PAD src0_sel:WORD_1 src1_sel:DWORD
	v_add3_u32 v19, v19, v22, s26
	v_add3_u32 v18, v18, v23, s26
	v_pk_mul_f32 v[26:27], v[40:41], v[26:27]
	v_add3_u32 v17, v24, v17, s26
	v_add3_u32 v5, v25, v5, s26
	v_and_b32_e32 v19, 0xffff0000, v19
	v_and_b32_e32 v18, 0xffff0000, v18
	v_and_b32_sdwa v22, v21, v150 dst_sel:DWORD dst_unused:UNUSED_PAD src0_sel:WORD_1 src1_sel:DWORD
	v_and_b32_sdwa v23, v20, v150 dst_sel:DWORD dst_unused:UNUSED_PAD src0_sel:WORD_1 src1_sel:DWORD
	v_or_b32_sdwa v19, v19, v5 dst_sel:DWORD dst_unused:UNUSED_PAD src0_sel:DWORD src1_sel:WORD_1
	v_or_b32_sdwa v18, v18, v17 dst_sel:DWORD dst_unused:UNUSED_PAD src0_sel:DWORD src1_sel:WORD_1
	v_and_b32_sdwa v5, v27, v150 dst_sel:DWORD dst_unused:UNUSED_PAD src0_sel:WORD_1 src1_sel:DWORD
	v_and_b32_sdwa v17, v26, v150 dst_sel:DWORD dst_unused:UNUSED_PAD src0_sel:WORD_1 src1_sel:DWORD
	v_add3_u32 v21, v21, v22, s26
	v_add3_u32 v20, v20, v23, s26
	v_add3_u32 v17, v26, v17, s26
	v_add3_u32 v5, v27, v5, s26
	v_and_b32_e32 v21, 0xffff0000, v21
	v_and_b32_e32 v20, 0xffff0000, v20
	v_cmp_lt_i32_e32 vcc, s36, v4
	v_or_b32_sdwa v21, v21, v5 dst_sel:DWORD dst_unused:UNUSED_PAD src0_sel:DWORD src1_sel:WORD_1
	v_or_b32_sdwa v20, v20, v17 dst_sel:DWORD dst_unused:UNUSED_PAD src0_sel:DWORD src1_sel:WORD_1
	s_or_b64 s[42:43], vcc, s[42:43]
	global_store_dwordx4 v[32:33], v[18:21], off
	s_andn2_b64 exec, exec, s[42:43]
	s_cbranch_execnz .LBB0_1052
